# adds: GDN scan chunk loads use the default cache policy instead of nt (the scan is a dependent-load latency pipeline; nt raised its per-step latency)
# baseline (speedup 1.0000x reference)
; #define SC_ISSUE(P, n) do { const int nn_ = (n) < 64 ? (n) : 63; const unsigned char* Gn_ = G0 + (size_t)nn_ * (8 * 40960); _Pragma("unroll") for (int mt = 0; mt < 4; ++mt) P[mt] = __builtin_nontemporal_load((const u32x4*)(Gn_ + mt * 8192 + tid * 16)); } while (0)
; #define SC_COMMIT(P, stage) do { LAS unsigned char* nb_ = lds + (stage) * 36864; _Pragma("unroll") for (int mt = 0; mt < 4; ++mt) *(LAS u32x4*)(nb_ + mt * 9216 + prow * 144 + pc * 16) = P[mt]; } while (0)
; #define SC_UNEXT(n) do { const int nn_ = (n) < 64 ? (n) : 63; const bf16* UT_ = (const bf16*)(G0 + (size_t)nn_ * (8 * 40960) + 32768); _Pragma("unroll") for (int mb = 0; mb < 4; ++mb) un[mb] = __builtin_nontemporal_load((const u32x2*)(UT_ + e * 64 + 16 * mb + 4 * q4)); gln = glast[(b * 64 + nn_) * 8 + h]; } while (0)
; DI void gdn_scan(int b, int h, const unsigned char* G, const float* glast, const bf16* PSg, const float* g_gdn, bf16* MIXA, LAS unsigned char* lds, int tid) {
;     ...
;     SC_ISSUE(pA, 0); SC_ISSUE(pB, 1);
;     SC_UNEXT(0);
;     SC_COMMIT(pA, 0);
;     __syncthreads();
.LBB0_818:
	s_ashr_i32 s3, s44, 3
	s_and_b32 s46, s44, 7
	s_lshl_b32 s22, s3, 9
	v_readfirstlane_b32 s20, v197
	s_or_b32 s0, s22, s46
	s_and_b32 s2, s43, 7
	s_lshr_b32 s10, s20, 2
	s_ashr_i32 s1, s0, 31
	s_mul_i32 s16, s0, 0xa000
	s_mul_hi_i32 s17, s0, 0xa000
	s_add_u32 s16, s80, s16
	s_addc_u32 s17, s81, s17
	v_lshl_add_u64 v[94:95], s[16:17], 0, v[80:81]
	s_waitcnt vmcnt(0)
	v_add_co_u32_e32 v8, vcc, s31, v94
	global_load_dwordx4 v[4:7], v[78:79], off
	global_load_dwordx4 v[0:3], v[78:79], off offset:16
	v_addc_co_u32_e32 v9, vcc, 0, v95, vcc
	global_load_dwordx4 v[24:27], v[94:95], off
	global_load_dwordx4 v[28:31], v[8:9], off
	v_add_co_u32_e32 v8, vcc, s34, v94
	v_and_or_b32 v44, s10, 48, v93
	s_nop 0
	v_addc_co_u32_e32 v9, vcc, 0, v95, vcc
	v_add_co_u32_e32 v10, vcc, s35, v94
	v_lshlrev_b32_e32 v76, 7, v44
	s_nop 0
	v_addc_co_u32_e32 v11, vcc, 0, v95, vcc
	global_load_dwordx4 v[32:35], v[8:9], off
	global_load_dwordx4 v[36:39], v[10:11], off
	v_add_co_u32_e32 v8, vcc, s36, v94
	v_lshl_add_u64 v[40:41], s[16:17], 0, v[76:77]
	s_nop 0
	v_addc_co_u32_e32 v9, vcc, 0, v95, vcc
	v_add_co_u32_e32 v12, vcc, s37, v94
	s_lshl_b64 s[0:1], s[0:1], 2
	s_nop 0
	v_addc_co_u32_e32 v13, vcc, 0, v95, vcc
	v_add_co_u32_e32 v16, vcc, s38, v94
	v_lshl_add_u64 v[40:41], v[40:41], 0, v[90:91]
	s_nop 0
	v_addc_co_u32_e32 v17, vcc, 0, v95, vcc
	v_add_co_u32_e32 v20, vcc, s39, v94
	s_add_u32 s0, s33, s0
	s_nop 0
	v_addc_co_u32_e32 v21, vcc, 0, v95, vcc
	v_lshl_add_u64 v[42:43], v[40:41], 0, s[12:13]
	v_add_co_u32_e32 v40, vcc, s40, v40
	s_addc_u32 s1, s96, s1
	global_load_dwordx4 v[8:11], v[8:9], off
	s_nop 0
	global_load_dwordx4 v[12:15], v[12:13], off
	s_nop 0
	global_load_dwordx4 v[16:19], v[16:17], off
	s_nop 0
	global_load_dwordx4 v[20:23], v[20:21], off
	v_addc_co_u32_e32 v41, vcc, 0, v41, vcc
	global_load_dword v102, v77, s[0:1]
	global_load_dwordx2 v[112:113], v[40:41], off
	global_load_dwordx2 v[110:111], v[42:43], off offset:32
	global_load_dwordx2 v[108:109], v[42:43], off offset:64
	global_load_dwordx2 v[106:107], v[42:43], off offset:96
	s_lshl_b32 s49, s3, 6
	s_cmpk_gt_u32 s20, 0xff
	s_cselect_b64 s[18:19], -1, 0
	s_lshl_b32 s47, s3, 12
	s_lshl_b32 s45, s46, 6
	s_lshl_b32 s10, s46, 7
	s_cmpk_lt_u32 s20, 0x100
	s_cselect_b64 s[20:21], -1, 0
	s_or_b32 s0, s22, s2
	s_or_b32 s22, s0, 8
	s_mul_hi_i32 s1, s0, 0xa000
	s_mul_i32 s0, s0, 0xa000
	v_lshlrev_b32_e32 v40, 6, v44
	v_lshlrev_b32_e32 v41, 1, v44
	s_mov_b32 s48, 0
	v_lshl_add_u64 v[96:97], v[82:83], 0, s[10:11]
	v_lshl_add_u64 v[98:99], v[84:85], 0, s[10:11]
	v_or_b32_e32 v137, s47, v103
	v_add_u32_e32 v138, v131, v41
	v_add_u32_e32 v139, v132, v41
	s_mov_b32 s50, 0
	s_waitcnt vmcnt(0)
	ds_write_b128 v133, v[24:27]
	ds_write_b128 v133, v[28:31] offset:9216
	ds_write_b128 v133, v[32:35] offset:18432
	ds_write_b128 v133, v[36:39] offset:27648
	v_or_b32_e32 v24, s0, v76
	v_mov_b32_e32 v25, s1
	v_lshl_add_u64 v[100:101], v[86:87], 0, v[24:25]
	s_mov_b64 s[0:1], 0
	v_lshlrev_b32_e32 v76, 1, v40
	v_mov_b32_e32 v24, v77
	v_mov_b32_e32 v25, v77
	v_mov_b32_e32 v26, v77
	v_mov_b32_e32 v27, v77
	v_mov_b32_e32 v28, v77
	v_mov_b32_e32 v29, v77
	v_mov_b32_e32 v30, v77
	v_mov_b32_e32 v31, v77
	v_mov_b32_e32 v32, v77
	v_mov_b32_e32 v33, v77
	v_mov_b32_e32 v34, v77
	v_mov_b32_e32 v35, v77
	v_mov_b32_e32 v36, v77
	v_mov_b32_e32 v37, v77
	v_mov_b32_e32 v38, v77
	v_mov_b32_e32 v39, v77
	s_waitcnt lgkmcnt(0)
	s_barrier
	s_branch .LBB0_820

; #define SC_ISSUE(P, n) do { const int nn_ = (n) < 64 ? (n) : 63; const unsigned char* Gn_ = G0 + (size_t)nn_ * (8 * 40960); _Pragma("unroll") for (int mt = 0; mt < 4; ++mt) P[mt] = __builtin_nontemporal_load((const u32x4*)(Gn_ + mt * 8192 + tid * 16)); } while (0)
; DI void gdn_scan(int b, int h, const unsigned char* G, const float* glast, const bf16* PSg, const float* g_gdn, bf16* MIXA, LAS unsigned char* lds, int tid) {
;     ...
;     for (int n = 0; n < 64; n += 2) {
;         SC_ISSUE(pA, n + 2);
.LBB0_820:
	s_cmp_gt_u32 s50, 61
	s_cselect_b64 s[26:27], -1, 0
	s_add_u32 s24, s0, 0xa0000
	s_addc_u32 s25, s1, 0
	s_cmp_lt_u32 s50, 62
	s_cselect_b32 s10, s24, 0x13b0000
	v_lshl_add_u64 v[48:49], v[94:95], 0, s[10:11]
	v_add_co_u32_e32 v44, vcc, s31, v48
	s_cmp_lg_u32 s48, 0
	s_nop 0
	v_addc_co_u32_e32 v45, vcc, 0, v49, vcc
	v_add_co_u32_e32 v50, vcc, 0x4000, v48
	global_load_dwordx4 v[40:43], v[48:49], off
	s_nop 0
	global_load_dwordx4 v[44:47], v[44:45], off
	v_addc_co_u32_e32 v51, vcc, 0, v49, vcc
	v_add_co_u32_e32 v52, vcc, 0x6000, v48
	s_cselect_b64 s[2:3], -1, 0
	s_nop 0
	v_addc_co_u32_e32 v53, vcc, 0, v49, vcc
	global_load_dwordx4 v[48:51], v[50:51], off
	s_nop 0
	global_load_dwordx4 v[52:55], v[52:53], off
	s_and_b64 s[52:53], s[2:3], s[18:19]
	s_mov_b64 s[2:3], -1
	s_and_b64 vcc, exec, s[52:53]
	v_add_u32_e32 v64, s48, v137
	s_cbranch_vccnz .LBB0_822
	v_add_u32_e32 v122, s48, v137
	s_mov_b64 s[2:3], 0

.LBB0_824:
	s_waitcnt vmcnt(9)
	s_nop 0
	v_add_u32_e32 v58, 32, v122
	v_ashrrev_i32_e32 v123, 31, v122
	v_ashrrev_i32_e32 v59, 31, v58
	v_lshlrev_b64 v[126:127], 11, v[122:123]
	v_lshlrev_b64 v[124:125], 11, v[58:59]
	s_ashr_i32 s23, s22, 31
	v_lshl_add_u64 v[56:57], v[96:97], 0, v[126:127]
	v_lshl_add_u64 v[58:59], v[96:97], 0, v[124:125]
	v_lshl_add_u64 v[64:65], v[100:101], 0, s[0:1]
	s_lshl_b64 s[0:1], s[22:23], 2
	global_load_dwordx4 v[60:63], v[56:57], off
	s_nop 0
	global_load_dwordx4 v[56:59], v[58:59], off
	s_nop 0
	global_load_dwordx2 v[120:121], v[64:65], off offset:-64
	global_load_dwordx2 v[118:119], v[64:65], off offset:-32
	global_load_dwordx2 v[116:117], v[64:65], off
	global_load_dwordx2 v[114:115], v[64:65], off offset:32
	s_add_u32 s0, s33, s0
	s_addc_u32 s1, s96, s1
	global_load_dword v104, v77, s[0:1]
	v_cndmask_b32_e64 v64, 0, 1, s[20:21]
	v_cmp_ne_u32_e64 s[0:1], 1, v64
	s_andn2_b64 vcc, exec, s[20:21]
	s_cbranch_vccnz .LBB0_826
	ds_read2_b64 v[168:171], v130 offset1:4
	v_add_u32_e32 v201, 0x800, v130
	ds_read2_b64 v[172:175], v201 offset0:32 offset1:36
	ds_read2_b64 v[176:179], v130 offset0:8 offset1:12
	ds_read2_b64 v[180:183], v201 offset0:40 offset1:44
	v_add_u32_e32 v202, 0x1000, v130
	ds_read2_b64 v[184:187], v202 offset0:64 offset1:68
	ds_read2_b64 v[188:191], v202 offset0:72 offset1:76
	v_add_u32_e32 v203, 0x1800, v130
	ds_read2_b64 v[192:195], v203 offset0:104 offset1:108
	ds_read2_b64 v[204:207], v203 offset0:96 offset1:100
	v_add_u32_e32 v201, 0x2000, v130
	ds_read2_b64 v[208:211], v201 offset0:128 offset1:132
	v_add_u32_e32 v202, 0x4800, v130
	ds_read2_b64 v[212:215], v202 offset1:4
	v_add_u32_e32 v75, 0x800, v130
	s_waitcnt vmcnt(15)
	v_lshlrev_b32_e32 v140, 16, v112
	v_and_b32_e32 v141, 0xffff0000, v112
	v_lshlrev_b32_e32 v142, 16, v113
	v_and_b32_e32 v143, 0xffff0000, v113
	v_cvt_pk_bf16_f32 v68, v24, v25
	v_cvt_pk_bf16_f32 v69, v26, v27
	v_cvt_pk_bf16_f32 v70, v28, v29
	v_cvt_pk_bf16_f32 v71, v30, v31
	v_add_u32_e32 v89, 0x1000, v130
	s_waitcnt lgkmcnt(9)
	v_mfma_f32_16x16x32_bf16 v[140:143], v[168:171], v[68:71], v[140:143]
	ds_read2_b64 v[216:219], v201 offset0:136 offset1:140
	s_waitcnt vmcnt(14)
	v_lshlrev_b32_e32 v72, 16, v110
	v_and_b32_e32 v73, 0xffff0000, v110
	v_lshlrev_b32_e32 v74, 16, v111
	v_and_b32_e32 v75, 0xffff0000, v111
	v_cvt_pk_bf16_f32 v64, v32, v33
	s_waitcnt lgkmcnt(9)
	v_mfma_f32_16x16x32_bf16 v[72:75], v[172:175], v[68:71], v[72:75]
	ds_read2_b64 v[220:223], v202 offset0:8 offset1:12
	v_cvt_pk_bf16_f32 v65, v34, v35
	v_cvt_pk_bf16_f32 v66, v36, v37
	v_cvt_pk_bf16_f32 v67, v38, v39
	s_waitcnt vmcnt(12)
	v_lshlrev_b32_e32 v152, 16, v106
	v_and_b32_e32 v153, 0xffff0000, v106
	s_waitcnt lgkmcnt(9)
	v_mfma_f32_16x16x32_bf16 v[140:143], v[176:179], v[64:67], v[140:143]
	v_add_u32_e32 v203, 0x2800, v130
	ds_read2_b64 v[224:227], v203 offset0:160 offset1:164
	v_lshlrev_b32_e32 v148, 16, v108
	v_and_b32_e32 v149, 0xffff0000, v108
	v_lshlrev_b32_e32 v150, 16, v109
	s_waitcnt lgkmcnt(9)
	v_mfma_f32_16x16x32_bf16 v[144:147], v[180:183], v[64:67], v[72:75]
	v_add_u32_e32 v201, 0x5000, v130
	ds_read2_b64 v[228:231], v201 offset0:32 offset1:36
	v_and_b32_e32 v151, 0xffff0000, v109
	v_lshlrev_b32_e32 v154, 16, v107
	v_and_b32_e32 v155, 0xffff0000, v107
	v_add_u32_e32 v89, 0x1800, v130
	s_waitcnt lgkmcnt(9)
	v_mfma_f32_16x16x32_bf16 v[108:111], v[184:187], v[68:71], v[148:151]
	ds_read2_b64 v[232:235], v203 offset0:168 offset1:172
	v_add_u32_e32 v106, 0x4800, v130
	v_add_u32_e32 v123, 0x5000, v130
	v_add_u32_e32 v89, 0x2000, v130
	s_waitcnt lgkmcnt(9)
	v_mfma_f32_16x16x32_bf16 v[108:111], v[188:191], v[64:67], v[108:111]
	ds_read2_b64 v[236:239], v201 offset0:40 offset1:44
	s_waitcnt vmcnt(11)
	v_pk_mul_f32 v[26:27], v[102:103], v[26:27] op_sel_hi:[0,1]
	v_pk_mul_f32 v[24:25], v[102:103], v[24:25] op_sel_hi:[0,1]
	v_pk_mul_f32 v[30:31], v[102:103], v[30:31] op_sel_hi:[0,1]
	s_waitcnt lgkmcnt(8)
	v_mfma_f32_16x16x32_bf16 v[72:75], v[204:207], v[68:71], v[152:155]
	v_add_u32_e32 v202, 0x3000, v130
	ds_read2_b64 v[240:243], v202 offset0:192 offset1:196
	s_nop 0
	v_cvt_pk_bf16_f32 v107, v110, v111
	v_pk_mul_f32 v[28:29], v[102:103], v[28:29] op_sel_hi:[0,1]
	s_waitcnt lgkmcnt(10)
	v_mfma_f32_16x16x32_bf16 v[152:155], v[192:195], v[64:67], v[72:75]
	v_add_u32_e32 v203, 0x5800, v130
	ds_read2_b64 v[244:247], v203 offset0:64 offset1:68
	v_pk_mul_f32 v[34:35], v[102:103], v[34:35] op_sel_hi:[0,1]
	v_pk_mul_f32 v[32:33], v[102:103], v[32:33] op_sel_hi:[0,1]
	v_cvt_pk_bf16_f32 v72, v140, v141
	v_cvt_pk_bf16_f32 v73, v142, v143
	s_waitcnt lgkmcnt(9)
	v_mfma_f32_16x16x32_bf16 v[140:143], v[208:211], v[68:71], 0
	ds_read2_b64 v[248:251], v202 offset0:200 offset1:204
	v_cvt_pk_bf16_f32 v74, v144, v145
	v_cvt_pk_bf16_f32 v75, v146, v147
	v_cvt_pk_bf16_f32 v106, v108, v109
	s_waitcnt lgkmcnt(9)
	v_mfma_f32_16x16x32_bf16 v[140:143], v[212:215], v[72:75], v[140:143]
	ds_read2_b64 v[168:171], v203 offset0:72 offset1:76
	v_cvt_pk_bf16_f32 v108, v152, v153
	v_cvt_pk_bf16_f32 v109, v154, v155
	v_pk_mul_f32 v[38:39], v[102:103], v[38:39] op_sel_hi:[0,1]
	s_waitcnt lgkmcnt(9)
	v_mfma_f32_16x16x32_bf16 v[140:143], v[216:219], v[64:67], v[140:143]
	v_add_u32_e32 v201, 0x3800, v130
	ds_read2_b64 v[172:175], v201 offset0:224 offset1:228
	v_mul_f32_e64 v36, v102, v36
	v_mul_f32_e64 v37, v102, v37
	s_waitcnt lgkmcnt(9)
	v_mfma_f32_16x16x32_bf16 v[110:113], v[220:223], v[106:109], v[140:143]
	v_add_u32_e32 v202, 0x6000, v130
	ds_read2_b64 v[176:179], v202 offset0:96 offset1:100
	s_nop 7
	v_cvt_pk_bf16_f32 v89, v110, s0
	ds_write_b16 v138, v89
	v_cvt_pk_bf16_f32 v89, v111, s0
	ds_write_b16 v138, v89 offset:144
	v_cvt_pk_bf16_f32 v89, v112, s0
	ds_write_b16 v138, v89 offset:288
	v_cvt_pk_bf16_f32 v89, v113, s0
	ds_write_b16 v138, v89 offset:432
	v_add_u32_e32 v89, 0x2800, v130
	s_waitcnt lgkmcnt(13)
; #define SC_ISSUE(P, n) do { const int nn_ = (n) < 64 ? (n) : 63; const unsigned char* Gn_ = G0 + (size_t)nn_ * (8 * 40960); _Pragma("unroll") for (int mt = 0; mt < 4; ++mt) P[mt] = __builtin_nontemporal_load((const u32x4*)(Gn_ + mt * 8192 + tid * 16)); } while (0)
; #define SC_COMMIT(P, stage) do { LAS unsigned char* nb_ = lds + (stage) * 36864; _Pragma("unroll") for (int mt = 0; mt < 4; ++mt) *(LAS u32x4*)(nb_ + mt * 9216 + prow * 144 + pc * 16) = P[mt]; } while (0)
; DI void gdn_scan(int b, int h, const unsigned char* G, const float* glast, const bf16* PSg, const float* g_gdn, bf16* MIXA, LAS unsigned char* lds, int tid) {
;     ...
;         SC_COMMIT(pB, 1);
;         __syncthreads();
;         SC_ISSUE(pB, n + 3);
	v_mfma_f32_16x16x32_bf16 v[110:113], v[224:227], v[68:71], 0
	ds_read2_b64 v[180:183], v201 offset0:232 offset1:236
	s_waitcnt lgkmcnt(13)
	v_mfma_f32_16x16x32_bf16 v[110:113], v[228:231], v[72:75], v[110:113]
	ds_read2_b64 v[184:187], v202 offset0:104 offset1:108
	s_waitcnt lgkmcnt(13)
	v_mfma_f32_16x16x32_bf16 v[110:113], v[232:235], v[64:67], v[110:113]
	v_add_u32_e32 v203, 0x6800, v130
	ds_read2_b64 v[188:191], v203 offset0:128 offset1:132
	v_add_u32_e32 v123, 0x5800, v130
	s_waitcnt lgkmcnt(13)
	v_mfma_f32_16x16x32_bf16 v[110:113], v[236:239], v[106:109], v[110:113]
	ds_read2_b64 v[192:195], v203 offset0:136 offset1:140
	s_nop 7
	v_cvt_pk_bf16_f32 v89, v110, s0
	ds_write_b16 v138, v89 offset:2304
	v_cvt_pk_bf16_f32 v89, v111, s0
	ds_write_b16 v138, v89 offset:2448
	v_cvt_pk_bf16_f32 v89, v112, s0
	ds_write_b16 v138, v89 offset:2592
	v_cvt_pk_bf16_f32 v89, v113, s0
	ds_write_b16 v138, v89 offset:2736
	v_add_u32_e32 v89, 0x3000, v130
	s_waitcnt lgkmcnt(15)
	v_mfma_f32_16x16x32_bf16 v[110:113], v[240:243], v[68:71], 0
	v_add_u32_e32 v201, 0x7000, v130
	ds_read2_b64 v[204:207], v201 offset0:160 offset1:164
	s_waitcnt lgkmcnt(15)
	v_mfma_f32_16x16x32_bf16 v[110:113], v[244:247], v[72:75], v[110:113]
	ds_read2_b64 v[208:211], v201 offset0:168 offset1:172
	s_waitcnt lgkmcnt(15)
	v_mfma_f32_16x16x32_bf16 v[110:113], v[248:251], v[64:67], v[110:113]
	v_add_u32_e32 v202, 0x7800, v130
	ds_read2_b64 v[212:215], v202 offset0:192 offset1:196
	v_add_u32_e32 v123, 0x6000, v130
	s_waitcnt lgkmcnt(15)
	v_mfma_f32_16x16x32_bf16 v[110:113], v[168:171], v[106:109], v[110:113]
	ds_read2_b64 v[216:219], v202 offset0:200 offset1:204
	s_nop 7
	v_cvt_pk_bf16_f32 v89, v110, s0
	ds_write_b16 v138, v89 offset:4608
	v_cvt_pk_bf16_f32 v89, v111, s0
	ds_write_b16 v138, v89 offset:4752
	v_cvt_pk_bf16_f32 v89, v112, s0
	ds_write_b16 v138, v89 offset:4896
	v_cvt_pk_bf16_f32 v89, v113, s0
	ds_write_b16 v138, v89 offset:5040
	v_add_u32_e32 v89, 0x3800, v130
	s_waitcnt lgkmcnt(15)
	v_mfma_f32_16x16x32_bf16 v[68:71], v[172:175], v[68:71], 0
	v_add_u32_e32 v203, 0x8000, v130
	ds_read2_b64 v[220:223], v203 offset0:224 offset1:228
	s_waitcnt lgkmcnt(15)
	v_mfma_f32_16x16x32_bf16 v[68:71], v[176:179], v[72:75], v[68:71]
	ds_read2_b64 v[224:227], v203 offset0:232 offset1:236
	s_waitcnt lgkmcnt(15)
	v_mfma_f32_16x16x32_bf16 v[64:67], v[180:183], v[64:67], v[68:71]
	s_nop 4
	s_waitcnt lgkmcnt(15)
	v_mfma_f32_16x16x32_bf16 v[64:67], v[184:187], v[106:109], v[64:67]
	v_add_u32_e32 v68, 0x6800, v130
	s_nop 6
	v_cvt_pk_bf16_f32 v64, v64, s0
	ds_write_b16 v138, v64 offset:6912
	v_cvt_pk_bf16_f32 v64, v65, s0
	ds_write_b16 v138, v64 offset:7056
	v_cvt_pk_bf16_f32 v64, v66, s0
	ds_write_b16 v138, v64 offset:7200
	v_cvt_pk_bf16_f32 v64, v67, s0
	ds_write_b16 v138, v64 offset:7344
	s_waitcnt lgkmcnt(15)
	v_mfma_f32_16x16x32_bf16 v[24:27], v[188:191], v[72:75], v[24:27]
	v_add_u32_e32 v68, 0x7000, v130
	s_waitcnt lgkmcnt(15)
	v_mfma_f32_16x16x32_bf16 v[24:27], v[192:195], v[106:109], v[24:27]
	s_waitcnt lgkmcnt(13)
	v_mfma_f32_16x16x32_bf16 v[28:31], v[204:207], v[72:75], v[28:31]
	v_add_u32_e32 v68, 0x7800, v130
	s_waitcnt lgkmcnt(12)
	v_mfma_f32_16x16x32_bf16 v[28:31], v[208:211], v[106:109], v[28:31]
	s_waitcnt lgkmcnt(11)
	v_mfma_f32_16x16x32_bf16 v[32:35], v[212:215], v[72:75], v[32:35]
	v_add_u32_e32 v68, 0x8000, v130
	s_waitcnt lgkmcnt(10)
	v_mfma_f32_16x16x32_bf16 v[32:35], v[216:219], v[106:109], v[32:35]
	s_waitcnt lgkmcnt(5)
	v_mfma_f32_16x16x32_bf16 v[36:39], v[220:223], v[72:75], v[36:39]
	s_waitcnt lgkmcnt(4)
	v_mfma_f32_16x16x32_bf16 v[36:39], v[224:227], v[106:109], v[36:39]
.LBB0_826:
	s_min_u32 s2, s50, 60
	s_mul_i32 s2, s2, 0x50000
	s_add_u32 s2, s16, s2
	s_addc_u32 s3, s17, 0
	ds_write_b128 v133, v[8:11] offset:36864
	ds_write_b128 v133, v[12:15] offset:46080
	ds_write_b128 v133, v[16:19] offset:55296
	ds_write_b128 v133, v[20:23] offset:64512
	v_lshl_add_u64 v[16:17], s[2:3], 0, v[80:81]
	v_add_co_u32_e32 v8, vcc, s42, v16
	s_waitcnt lgkmcnt(0)
	s_nop 0
	v_addc_co_u32_e32 v9, vcc, 0, v17, vcc
	v_add_co_u32_e32 v12, vcc, 0xf2000, v16
	s_barrier
	s_nop 0
	v_addc_co_u32_e32 v13, vcc, 0, v17, vcc
	v_add_co_u32_e32 v18, vcc, 0xf4000, v16
	s_nop 1
	v_addc_co_u32_e32 v19, vcc, 0, v17, vcc
	v_add_co_u32_e32 v20, vcc, 0xf6000, v16
	global_load_dwordx4 v[8:11], v[8:9], off
	s_nop 0
	global_load_dwordx4 v[12:15], v[12:13], off
	v_addc_co_u32_e32 v21, vcc, 0, v17, vcc
	global_load_dwordx4 v[16:19], v[18:19], off
	s_nop 0
	global_load_dwordx4 v[20:23], v[20:21], off
	v_cndmask_b32_e64 v64, 0, 1, s[18:19]
	v_cmp_ne_u32_e64 s[2:3], 1, v64
	s_andn2_b64 vcc, exec, s[18:19]
	s_cbranch_vccnz .LBB0_828
	v_and_b32_e32 v65, 64, v136
	v_xor_b32_e32 v64, 1, v136
	v_add_u32_e32 v68, 64, v65
	v_cmp_lt_i32_e32 vcc, v64, v68
	v_xor_b32_e32 v69, 4, v136
	s_waitcnt vmcnt(10)
	v_lshlrev_b32_e32 v112, 16, v61
	v_cndmask_b32_e32 v64, v136, v64, vcc
	v_lshlrev_b32_e32 v89, 2, v64
	v_xor_b32_e32 v64, 2, v136
	v_cmp_lt_i32_e32 vcc, v64, v68
	v_and_b32_e32 v113, 0xffff0000, v61
	v_mul_f32_e32 v61, 0xbfb8aa3b, v112
	v_cndmask_b32_e32 v64, v136, v64, vcc
	v_lshlrev_b32_e32 v102, 2, v64
	ds_read_b128 v[64:67], v134
	v_cmp_lt_i32_e32 vcc, v69, v68
	v_exp_f32_e32 v61, v61
	v_mul_f32_e32 v140, 0xbfb8aa3b, v113
	v_cndmask_b32_e32 v68, v136, v69, vcc
	v_lshlrev_b32_e32 v123, 2, v68
	ds_read_b128 v[68:71], v134 offset:4608
	s_waitcnt lgkmcnt(1)
	v_lshlrev_b32_e32 v108, 16, v66
	v_and_b32_e32 v109, 0xffff0000, v66
	v_lshlrev_b32_e32 v66, 16, v62
	v_lshlrev_b32_e32 v72, 16, v67
	v_and_b32_e32 v73, 0xffff0000, v67
	v_and_b32_e32 v67, 0xffff0000, v62
	v_mul_f32_e32 v62, 0xbfb8aa3b, v66
	v_exp_f32_e32 v110, v62
	v_mul_f32_e32 v62, 0xbfb8aa3b, v67
	v_exp_f32_e32 v111, v62
	v_exp_f32_e32 v140, v140
	v_add_f32_e32 v110, 1.0, v110
	v_rcp_f32_e32 v110, v110
	v_add_f32_e32 v111, 1.0, v111
	v_rcp_f32_e32 v111, v111
	v_add_f32_e32 v61, 1.0, v61
	v_and_b32_e32 v141, 0xffff0000, v65
	v_lshlrev_b32_e32 v74, 16, v63
	v_pk_mul_f32 v[66:67], v[110:111], v[66:67]
	v_rcp_f32_e32 v110, v61
	v_add_f32_e32 v61, 1.0, v140
	v_rcp_f32_e32 v111, v61
	v_lshlrev_b32_e32 v140, 16, v65
	v_and_b32_e32 v75, 0xffff0000, v63
	v_mul_f32_e32 v145, 0xbfb8aa3b, v75
	v_pk_mul_f32 v[110:111], v[110:111], v[112:113]
	v_lshlrev_b32_e32 v112, 16, v60
	v_and_b32_e32 v113, 0xffff0000, v60
	v_mul_f32_e32 v60, 0xbfb8aa3b, v112
	v_exp_f32_e32 v61, v60
	v_mul_f32_e32 v60, 0xbfb8aa3b, v113
	v_exp_f32_e32 v65, v60
	v_exp_f32_e32 v147, v145
	v_add_f32_e32 v61, 1.0, v61
	v_rcp_f32_e32 v144, v61
	v_add_f32_e32 v61, 1.0, v65
	v_mul_f32_e32 v65, 0xbfb8aa3b, v74
	v_exp_f32_e32 v65, v65
	v_rcp_f32_e32 v145, v61
	s_waitcnt vmcnt(9)
	v_lshlrev_b32_e32 v156, 16, v57
	v_lshlrev_b32_e32 v60, 16, v64
	v_add_f32_e32 v61, 1.0, v65
	v_rcp_f32_e32 v146, v61
	v_add_f32_e32 v61, 1.0, v147
	v_rcp_f32_e32 v147, v61
	v_and_b32_e32 v61, 0xffff0000, v64
	v_mul_f32_e32 v155, 0xbfb8aa3b, v156
	s_waitcnt lgkmcnt(0)
	v_lshlrev_b32_e32 v164, 16, v68
	v_and_b32_e32 v165, 0xffff0000, v68
	v_pk_mul_f32 v[64:65], v[60:61], v[60:61]
	v_lshlrev_b32_e32 v150, 16, v70
	v_and_b32_e32 v151, 0xffff0000, v70
	v_lshlrev_b32_e32 v70, 16, v58
	v_lshlrev_b32_e32 v154, 16, v69
	v_exp_f32_e32 v159, v155
	v_and_b32_e32 v155, 0xffff0000, v69
	v_pk_mul_f32 v[68:69], v[164:165], v[164:165]
	v_pk_mul_f32 v[142:143], v[140:141], v[140:141]
	v_pk_mul_f32 v[112:113], v[144:145], v[112:113]
	v_lshlrev_b32_e32 v144, 16, v71
	v_and_b32_e32 v145, 0xffff0000, v71
	v_and_b32_e32 v71, 0xffff0000, v58
	v_mul_f32_e32 v58, 0xbfb8aa3b, v70
	v_pk_mul_f32 v[160:161], v[154:155], v[154:155]
	v_mov_b32_e32 v166, v68
	v_mov_b32_e32 v167, v64
	v_mov_b32_e32 v64, v69
	v_exp_f32_e32 v152, v58
	v_mul_f32_e32 v58, 0xbfb8aa3b, v71
	v_pk_add_f32 v[64:65], v[166:167], v[64:65]
	v_mov_b32_e32 v68, v160
	v_mov_b32_e32 v69, v142
	v_pk_mul_f32 v[62:63], v[108:109], v[108:109]
	v_pk_mul_f32 v[74:75], v[146:147], v[74:75]
	v_lshlrev_b32_e32 v146, 16, v59
	v_and_b32_e32 v147, 0xffff0000, v59
	v_exp_f32_e32 v153, v58
	v_pk_mul_f32 v[58:59], v[150:151], v[150:151]
	v_pk_add_f32 v[64:65], v[68:69], v[64:65]
	v_mov_b32_e32 v142, v161
	v_pk_add_f32 v[64:65], v[142:143], v[64:65]
	v_mov_b32_e32 v68, v58
	v_mov_b32_e32 v69, v62
	v_pk_mul_f32 v[106:107], v[72:73], v[72:73]
	v_pk_mul_f32 v[148:149], v[144:145], v[144:145]
	v_pk_add_f32 v[64:65], v[68:69], v[64:65]
	v_mov_b32_e32 v62, v59
	v_pk_add_f32 v[58:59], v[62:63], v[64:65]
	v_mov_b32_e32 v62, v148
	v_mov_b32_e32 v63, v106
	v_and_b32_e32 v157, 0xffff0000, v57
	v_add_f32_e32 v57, 1.0, v159
	v_pk_add_f32 v[58:59], v[62:63], v[58:59]
	v_mov_b32_e32 v106, v149
	v_rcp_f32_e32 v162, v57
	v_mul_f32_e32 v57, 0xbfb8aa3b, v157
	v_pk_add_f32 v[58:59], v[106:107], v[58:59]
	v_exp_f32_e32 v57, v57
	ds_bpermute_b32 v63, v89, v59
	ds_bpermute_b32 v62, v89, v58
	v_lshlrev_b32_e32 v64, 16, v56
	v_add_f32_e32 v57, 1.0, v57
	v_rcp_f32_e32 v163, v57
	v_and_b32_e32 v65, 0xffff0000, v56
	s_waitcnt lgkmcnt(0)
	v_pk_add_f32 v[56:57], v[58:59], v[62:63]
	ds_bpermute_b32 v59, v102, v57
	ds_bpermute_b32 v58, v102, v56
	v_mul_f32_e32 v62, 0xbfb8aa3b, v64
	v_mul_f32_e32 v63, 0xbfb8aa3b, v65
	v_exp_f32_e32 v62, v62
	v_exp_f32_e32 v63, v63
	s_waitcnt lgkmcnt(0)
	v_pk_add_f32 v[56:57], v[56:57], v[58:59]
	ds_bpermute_b32 v59, v123, v57
	ds_bpermute_b32 v58, v123, v56
	v_add_f32_e32 v62, 1.0, v62
	v_add_f32_e32 v63, 1.0, v63
	v_rcp_f32_e32 v62, v62
	v_rcp_f32_e32 v63, v63
	s_waitcnt lgkmcnt(0)
	v_pk_add_f32 v[56:57], v[56:57], v[58:59]
	v_lshl_add_u64 v[126:127], v[98:99], 0, v[126:127]
	v_pk_fma_f32 v[58:59], v[56:57], s[14:15], v[92:93] op_sel_hi:[1,0,0]
	v_pk_mul_f32 v[62:63], v[62:63], v[64:65]
	v_mul_f32_e32 v56, 0x4b800000, v59
	v_cmp_gt_f32_e32 vcc, s41, v59
	v_add_f32_e32 v152, 1.0, v152
	v_add_f32_e32 v153, 1.0, v153
	v_cndmask_b32_e32 v56, v59, v56, vcc
	v_rsq_f32_e32 v56, v56
	v_mul_f32_e32 v59, 0x4b800000, v58
	v_rcp_f32_e32 v152, v152
	v_rcp_f32_e32 v153, v153
	v_mul_f32_e32 v57, 0x45800000, v56
	v_cndmask_b32_e32 v56, v56, v57, vcc
	v_pk_mul_f32 v[60:61], v[56:57], v[60:61] op_sel_hi:[0,1]
	v_pk_mul_f32 v[60:61], v[4:5], v[60:61]
	v_pk_mul_f32 v[64:65], v[56:57], v[140:141] op_sel_hi:[0,1]
	v_pk_mul_f32 v[106:107], v[56:57], v[108:109] op_sel_hi:[0,1]
	v_pk_mul_f32 v[56:57], v[56:57], v[72:73] op_sel_hi:[0,1]
	v_cmp_gt_f32_e32 vcc, s41, v58
	v_pk_mul_f32 v[60:61], v[112:113], v[60:61]
	v_pk_mul_f32 v[56:57], v[2:3], v[56:57]
	v_cndmask_b32_e32 v58, v58, v59, vcc
	v_pk_mul_f32 v[72:73], v[74:75], v[56:57]
	v_cvt_pk_bf16_f32 v56, v60, v61
	v_rsq_f32_e32 v60, v58
	v_pk_mul_f32 v[64:65], v[6:7], v[64:65]
	v_pk_mul_f32 v[106:107], v[0:1], v[106:107]
	v_pk_mul_f32 v[64:65], v[110:111], v[64:65]
	v_pk_mul_f32 v[66:67], v[66:67], v[106:107]
	v_cvt_pk_bf16_f32 v57, v64, v65
	v_cvt_pk_bf16_f32 v58, v66, v67
	v_cvt_pk_bf16_f32 v59, v72, v73
	global_store_dwordx4 v[126:127], v[56:59], off offset:1024
	v_mul_f32_e32 v64, 0xbfb8aa3b, v147
	v_exp_f32_e32 v65, v64
	v_mul_f32_e32 v56, 0x45800000, v60
	v_cndmask_b32_e32 v56, v60, v56, vcc
	v_pk_mul_f32 v[58:59], v[56:57], v[164:165] op_sel_hi:[0,1]
	v_pk_mul_f32 v[58:59], v[4:5], v[58:59]
	v_pk_mul_f32 v[60:61], v[56:57], v[154:155] op_sel_hi:[0,1]
	v_pk_mul_f32 v[58:59], v[62:63], v[58:59]
	v_pk_mul_f32 v[62:63], v[56:57], v[150:151] op_sel_hi:[0,1]
	v_mul_f32_e32 v57, 0xbfb8aa3b, v146
	v_exp_f32_e32 v57, v57
	v_pk_mul_f32 v[68:69], v[152:153], v[70:71]
	v_pk_mul_f32 v[70:71], v[162:163], v[156:157]
	v_pk_mul_f32 v[60:61], v[6:7], v[60:61]
	v_add_f32_e32 v57, 1.0, v57
	v_rcp_f32_e32 v64, v57
	v_add_f32_e32 v57, 1.0, v65
	v_rcp_f32_e32 v65, v57
	v_pk_mul_f32 v[56:57], v[56:57], v[144:145] op_sel_hi:[0,1]
	v_pk_mul_f32 v[62:63], v[0:1], v[62:63]
	v_pk_mul_f32 v[56:57], v[2:3], v[56:57]
	v_pk_mul_f32 v[64:65], v[64:65], v[146:147]
	v_pk_mul_f32 v[60:61], v[70:71], v[60:61]
	v_pk_mul_f32 v[62:63], v[68:69], v[62:63]
	v_pk_mul_f32 v[64:65], v[64:65], v[56:57]
	v_cvt_pk_bf16_f32 v56, v58, v59
	v_cvt_pk_bf16_f32 v57, v60, v61
	v_cvt_pk_bf16_f32 v58, v62, v63
	v_cvt_pk_bf16_f32 v59, v64, v65
	v_lshl_add_u64 v[60:61], v[98:99], 0, v[124:125]
	global_store_dwordx4 v[60:61], v[56:59], off offset:1024
.LBB0_828:
	s_min_u32 s10, s50, 61
	s_add_i32 s10, s10, 2
	s_mul_i32 s23, s10, 0x50000
	s_add_u32 s52, s16, s23
	s_addc_u32 s53, s17, 0
	s_add_i32 s10, s10, s49
	s_waitcnt vmcnt(9)
	v_add_u32_e32 v56, 64, v122
	v_add_u32_e32 v58, 0x60, v122
	v_lshl_add_u64 v[64:65], s[52:53], 0, v[76:77]
	v_mov_b32_e32 v89, v77
	s_lshl_b32 s10, s10, 3
	v_ashrrev_i32_e32 v57, 31, v56
	v_ashrrev_i32_e32 v59, 31, v58
	v_lshl_add_u64 v[64:65], v[64:65], 0, v[88:89]
	s_or_b32 s52, s10, s46
	v_lshlrev_b64 v[56:57], 11, v[56:57]
	v_lshlrev_b64 v[58:59], 11, v[58:59]
	v_lshl_add_u64 v[66:67], v[64:65], 0, s[12:13]
	v_add_co_u32_e32 v64, vcc, s40, v64
	s_ashr_i32 s53, s52, 31
	v_lshl_add_u64 v[56:57], v[96:97], 0, v[56:57]
	v_lshl_add_u64 v[58:59], v[96:97], 0, v[58:59]
	v_addc_co_u32_e32 v65, vcc, 0, v65, vcc
	s_lshl_b64 s[52:53], s[52:53], 2
	global_load_dwordx4 v[60:63], v[56:57], off
	s_nop 0
	global_load_dwordx4 v[56:59], v[58:59], off
	s_nop 0
	global_load_dwordx2 v[112:113], v[64:65], off
	global_load_dwordx2 v[110:111], v[66:67], off offset:32
	global_load_dwordx2 v[108:109], v[66:67], off offset:64
	global_load_dwordx2 v[106:107], v[66:67], off offset:96
	s_add_u32 s52, s33, s52
	s_addc_u32 s53, s96, s53
	global_load_dword v102, v77, s[52:53]
	s_and_b64 vcc, exec, s[0:1]
	s_cbranch_vccnz .LBB0_819
	v_add_u32_e32 v201, 0x9000, v130
	ds_read2_b64 v[168:171], v201 offset1:4
	v_add_u32_e32 v202, 0x9800, v130
	ds_read2_b64 v[172:175], v202 offset0:32 offset1:36
	ds_read2_b64 v[176:179], v201 offset0:8 offset1:12
	v_add_u32_e32 v203, 0xa000, v130
	ds_read2_b64 v[180:183], v203 offset0:64 offset1:68
	ds_read2_b64 v[184:187], v202 offset0:40 offset1:44
	ds_read2_b64 v[188:191], v203 offset0:72 offset1:76
	v_add_u32_e32 v201, 0xa800, v130
	ds_read2_b64 v[192:195], v201 offset0:96 offset1:100
	ds_read2_b64 v[204:207], v201 offset0:104 offset1:108
	v_add_u32_e32 v202, 0xb000, v130
	ds_read2_b64 v[208:211], v202 offset0:128 offset1:132
	v_add_u32_e32 v203, 0xd800, v130
	ds_read2_b64 v[212:215], v203 offset1:4
	v_add_u32_e32 v64, 0x9000, v130
	v_add_u32_e32 v75, 0x9800, v130
	s_waitcnt vmcnt(15)
	v_lshlrev_b32_e32 v122, 16, v120
	v_and_b32_e32 v123, 0xffff0000, v120
	v_lshlrev_b32_e32 v124, 16, v121
	v_and_b32_e32 v125, 0xffff0000, v121
	v_cvt_pk_bf16_f32 v68, v24, v25
	v_cvt_pk_bf16_f32 v69, v26, v27
	v_cvt_pk_bf16_f32 v70, v28, v29
	v_cvt_pk_bf16_f32 v71, v30, v31
	v_add_u32_e32 v89, 0xa000, v130
	s_waitcnt lgkmcnt(9)
	v_mfma_f32_16x16x32_bf16 v[120:123], v[168:171], v[68:71], v[122:125]
	ds_read2_b64 v[216:219], v202 offset0:136 offset1:140
	s_waitcnt vmcnt(14)
	v_lshlrev_b32_e32 v72, 16, v118
	v_and_b32_e32 v73, 0xffff0000, v118
	v_lshlrev_b32_e32 v74, 16, v119
	v_and_b32_e32 v75, 0xffff0000, v119
	v_cvt_pk_bf16_f32 v64, v32, v33
	v_cvt_pk_bf16_f32 v65, v34, v35
	s_waitcnt lgkmcnt(9)
	v_mfma_f32_16x16x32_bf16 v[72:75], v[172:175], v[68:71], v[72:75]
	ds_read2_b64 v[220:223], v203 offset0:8 offset1:12
	v_cvt_pk_bf16_f32 v66, v36, v37
	v_cvt_pk_bf16_f32 v67, v38, v39
	s_waitcnt vmcnt(11)
	v_pk_mul_f32 v[26:27], v[104:105], v[26:27] op_sel_hi:[0,1]
	v_pk_mul_f32 v[24:25], v[104:105], v[24:25] op_sel_hi:[0,1]
	s_waitcnt lgkmcnt(9)
	v_mfma_f32_16x16x32_bf16 v[120:123], v[176:179], v[64:67], v[120:123]
	v_add_u32_e32 v201, 0xb800, v130
	ds_read2_b64 v[224:227], v201 offset0:160 offset1:164
	v_lshlrev_b32_e32 v144, 16, v116
	v_and_b32_e32 v145, 0xffff0000, v116
	v_lshlrev_b32_e32 v146, 16, v117
	s_waitcnt lgkmcnt(8)
	v_mfma_f32_16x16x32_bf16 v[124:127], v[184:187], v[64:67], v[72:75]
	v_add_u32_e32 v202, 0xe000, v130
	ds_read2_b64 v[228:231], v202 offset0:32 offset1:36
	v_and_b32_e32 v147, 0xffff0000, v117
	v_pk_mul_f32 v[30:31], v[104:105], v[30:31] op_sel_hi:[0,1]
	v_pk_mul_f32 v[28:29], v[104:105], v[28:29] op_sel_hi:[0,1]
	v_add_u32_e32 v89, 0xa800, v130
	s_waitcnt lgkmcnt(10)
	v_mfma_f32_16x16x32_bf16 v[116:119], v[180:183], v[68:71], v[144:147]
	ds_read2_b64 v[232:235], v201 offset0:168 offset1:172
	v_add_u32_e32 v89, 0xb000, v130
	v_lshlrev_b32_e32 v144, 16, v114
	v_and_b32_e32 v145, 0xffff0000, v114
	v_lshlrev_b32_e32 v146, 16, v115
	v_and_b32_e32 v147, 0xffff0000, v115
	s_waitcnt lgkmcnt(9)
	v_mfma_f32_16x16x32_bf16 v[116:119], v[188:191], v[64:67], v[116:119]
	ds_read2_b64 v[236:239], v202 offset0:40 offset1:44
	v_add_u32_e32 v114, 0xd800, v130
	v_pk_mul_f32 v[34:35], v[104:105], v[34:35] op_sel_hi:[0,1]
	v_pk_mul_f32 v[32:33], v[104:105], v[32:33] op_sel_hi:[0,1]
	s_waitcnt lgkmcnt(9)
	v_mfma_f32_16x16x32_bf16 v[72:75], v[192:195], v[68:71], v[144:147]
	v_add_u32_e32 v203, 0xc000, v130
	ds_read2_b64 v[240:243], v203 offset0:192 offset1:196
	s_nop 1
	v_cvt_pk_bf16_f32 v115, v118, v119
	v_pk_mul_f32 v[38:39], v[104:105], v[38:39] op_sel_hi:[0,1]
	s_waitcnt lgkmcnt(9)
	v_mfma_f32_16x16x32_bf16 v[144:147], v[204:207], v[64:67], v[72:75]
	v_add_u32_e32 v201, 0xe800, v130
	ds_read2_b64 v[244:247], v201 offset0:64 offset1:68
	v_pk_mul_f32 v[36:37], v[104:105], v[36:37] op_sel_hi:[0,1]
	s_nop 0
	v_cvt_pk_bf16_f32 v72, v120, v121
	v_cvt_pk_bf16_f32 v73, v122, v123
	s_waitcnt lgkmcnt(9)
	v_mfma_f32_16x16x32_bf16 v[120:123], v[208:211], v[68:71], 0
	ds_read2_b64 v[248:251], v203 offset0:200 offset1:204
	v_cvt_pk_bf16_f32 v74, v124, v125
	v_cvt_pk_bf16_f32 v75, v126, v127
	v_cvt_pk_bf16_f32 v114, v116, v117
	s_waitcnt lgkmcnt(9)
	v_mfma_f32_16x16x32_bf16 v[120:123], v[212:215], v[72:75], v[120:123]
	ds_read2_b64 v[168:171], v201 offset0:72 offset1:76
	v_cvt_pk_bf16_f32 v116, v144, v145
	v_cvt_pk_bf16_f32 v117, v146, v147
	s_waitcnt lgkmcnt(9)
	v_mfma_f32_16x16x32_bf16 v[120:123], v[216:219], v[64:67], v[120:123]
	v_add_u32_e32 v202, 0xc800, v130
	ds_read2_b64 v[172:175], v202 offset0:224 offset1:228
	s_waitcnt lgkmcnt(9)
	v_mfma_f32_16x16x32_bf16 v[118:121], v[220:223], v[114:117], v[120:123]
	v_add_u32_e32 v203, 0xf000, v130
	ds_read2_b64 v[176:179], v203 offset0:96 offset1:100
	v_add_u32_e32 v126, 0xe000, v130
	s_nop 6
	v_cvt_pk_bf16_f32 v89, v118, s0
	ds_write_b16 v139, v89
	v_cvt_pk_bf16_f32 v89, v119, s0
	ds_write_b16 v139, v89 offset:144
	v_cvt_pk_bf16_f32 v89, v120, s0
	ds_write_b16 v139, v89 offset:288
	v_cvt_pk_bf16_f32 v89, v121, s0
	ds_write_b16 v139, v89 offset:432
	v_add_u32_e32 v89, 0xb800, v130
	s_waitcnt lgkmcnt(13)
	v_mfma_f32_16x16x32_bf16 v[118:121], v[224:227], v[68:71], 0
	ds_read2_b64 v[180:183], v202 offset0:232 offset1:236
	s_waitcnt lgkmcnt(13)
	v_mfma_f32_16x16x32_bf16 v[118:121], v[228:231], v[72:75], v[118:121]
	ds_read2_b64 v[184:187], v203 offset0:104 offset1:108
	s_waitcnt lgkmcnt(13)
	v_mfma_f32_16x16x32_bf16 v[118:121], v[232:235], v[64:67], v[118:121]
	v_add_u32_e32 v201, 0xf800, v130
	ds_read2_b64 v[188:191], v201 offset0:128 offset1:132
	v_add_u32_e32 v126, 0xe800, v130
	s_waitcnt lgkmcnt(13)
	v_mfma_f32_16x16x32_bf16 v[118:121], v[236:239], v[114:117], v[118:121]
	ds_read2_b64 v[192:195], v201 offset0:136 offset1:140
	s_nop 7
	v_cvt_pk_bf16_f32 v89, v118, s0
	ds_write_b16 v139, v89 offset:2304
	v_cvt_pk_bf16_f32 v89, v119, s0
	ds_write_b16 v139, v89 offset:2448
	v_cvt_pk_bf16_f32 v89, v120, s0
	ds_write_b16 v139, v89 offset:2592
	v_cvt_pk_bf16_f32 v89, v121, s0
	ds_write_b16 v139, v89 offset:2736
	v_add_u32_e32 v89, 0xc000, v130
	s_waitcnt lgkmcnt(15)
	v_mfma_f32_16x16x32_bf16 v[118:121], v[240:243], v[68:71], 0
	v_add_u32_e32 v202, 0x800, v135
	ds_read2_b64 v[204:207], v202 offset0:32 offset1:36
	s_waitcnt lgkmcnt(15)
	v_mfma_f32_16x16x32_bf16 v[118:121], v[244:247], v[72:75], v[118:121]
	ds_read2_b64 v[208:211], v202 offset0:40 offset1:44
	s_waitcnt lgkmcnt(15)
	v_mfma_f32_16x16x32_bf16 v[118:121], v[248:251], v[64:67], v[118:121]
	v_add_u32_e32 v203, 0x1000, v135
	ds_read2_b64 v[212:215], v203 offset0:64 offset1:68
	s_waitcnt lgkmcnt(15)
	v_mfma_f32_16x16x32_bf16 v[118:121], v[168:171], v[114:117], v[118:121]
	ds_read2_b64 v[216:219], v203 offset0:72 offset1:76
	v_add_u32_e32 v122, 0xf000, v130
	s_nop 6
	v_cvt_pk_bf16_f32 v89, v118, s0
	ds_write_b16 v139, v89 offset:4608
	v_cvt_pk_bf16_f32 v89, v119, s0
	ds_write_b16 v139, v89 offset:4752
	v_cvt_pk_bf16_f32 v89, v120, s0
	ds_write_b16 v139, v89 offset:4896
	v_cvt_pk_bf16_f32 v89, v121, s0
	ds_write_b16 v139, v89 offset:5040
	v_add_u32_e32 v89, 0xc800, v130
	s_waitcnt lgkmcnt(15)
	v_mfma_f32_16x16x32_bf16 v[68:71], v[172:175], v[68:71], 0
	v_add_u32_e32 v201, 0x1800, v135
	ds_read2_b64 v[220:223], v201 offset0:96 offset1:100
	s_waitcnt lgkmcnt(15)
	v_mfma_f32_16x16x32_bf16 v[68:71], v[176:179], v[72:75], v[68:71]
	ds_read2_b64 v[224:227], v201 offset0:104 offset1:108
	s_waitcnt lgkmcnt(15)
	v_mfma_f32_16x16x32_bf16 v[64:67], v[180:183], v[64:67], v[68:71]
	s_nop 4
	s_waitcnt lgkmcnt(15)
	v_mfma_f32_16x16x32_bf16 v[64:67], v[184:187], v[114:117], v[64:67]
	v_add_u32_e32 v68, 0xf800, v130
	s_nop 6
	v_cvt_pk_bf16_f32 v64, v64, s0
	ds_write_b16 v139, v64 offset:6912
	v_cvt_pk_bf16_f32 v64, v65, s0
	ds_write_b16 v139, v64 offset:7056
	v_cvt_pk_bf16_f32 v64, v66, s0
	ds_write_b16 v139, v64 offset:7200
	v_cvt_pk_bf16_f32 v64, v67, s0
	ds_write_b16 v139, v64 offset:7344
	s_waitcnt lgkmcnt(15)
	v_mfma_f32_16x16x32_bf16 v[24:27], v[188:191], v[72:75], v[24:27]
	v_add_u32_e32 v68, 0x800, v135
	s_waitcnt lgkmcnt(15)
	v_mfma_f32_16x16x32_bf16 v[24:27], v[192:195], v[114:117], v[24:27]
	s_waitcnt lgkmcnt(13)
	v_mfma_f32_16x16x32_bf16 v[28:31], v[204:207], v[72:75], v[28:31]
	v_add_u32_e32 v68, 0x1000, v135
	s_waitcnt lgkmcnt(12)
	v_mfma_f32_16x16x32_bf16 v[28:31], v[208:211], v[114:117], v[28:31]
	s_waitcnt lgkmcnt(11)
	v_mfma_f32_16x16x32_bf16 v[32:35], v[212:215], v[72:75], v[32:35]
	v_add_u32_e32 v68, 0x1800, v135
	s_waitcnt lgkmcnt(10)
	v_mfma_f32_16x16x32_bf16 v[32:35], v[216:219], v[114:117], v[32:35]
	s_waitcnt lgkmcnt(5)
	v_mfma_f32_16x16x32_bf16 v[36:39], v[220:223], v[72:75], v[36:39]
	s_waitcnt lgkmcnt(4)
	v_mfma_f32_16x16x32_bf16 v[36:39], v[224:227], v[114:117], v[36:39]
	s_branch .LBB0_819
